# phase 7 tile epilogue: two warm-up loads per lane cover all lines of the wave's x sub-tile so the 64 dependent element loads hit L2
# speedup vs baseline: 1.0320x; 1.0133x over previous
; DI const float* xrow_ptr(const Params& p, int l, int row) {
;   if (l > 0) return p.out + (size_t)row * D;
;   return row < NP ? p.in[0] + (size_t)row * D : p.in[1] + (size_t)(row - NP) * D;
; }
; DI void phase7(const Params& p, int l, unsigned char* smem) {
;     ...
;     foreach_acc(acc, m0, n0, [&](int row, int col, float v) {
;       float xo = xrow_ptr(p, l, row)[col];
;       float gt = mod[(l * 10 + bidx_of(row)) * 3072 + 2048 + col];
;       p.out[(size_t)row * D + col] = xo + gt * v;
;     });
.LBB0_1013:
	v_subrev_u32_e32 v72, s0, v72
	v_and_or_b32 v72, v72, 40, v242
	ds_read_b64 v[72:73], v72
	v_and_b32_e32 v65, 64, v65
	v_and_b32_e32 v64, 31, v64
	v_or3_b32 v162, v64, v65, s46
	v_lshlrev_b64 v[70:71], 12, v[70:71]
	v_lshlrev_b64 v[74:75], 2, v[162:163]
	v_cmp_gt_i32_e32 vcc, s50, v66
	v_ashrrev_i32_e32 v121, 13, v122
	v_add_u32_e32 v120, 0x800, v162
	v_readlane_b32 s2, v254, 37
	v_readlane_b32 s3, v254, 38
	v_lshlrev_b64 v[68:69], 12, v[68:69]
	v_or_b32_e32 v124, 1, v123
	v_lshl_add_u64 v[64:65], s[2:3], 0, v[74:75]
	v_lshl_add_u64 v[68:69], v[64:65], 0, v[68:69]
	v_cmp_lt_i32_e64 s[8:9], s64, v66
	s_mov_b64 s[2:3], -1
	s_waitcnt lgkmcnt(0)
	v_lshl_add_u64 v[70:71], v[72:73], 0, v[70:71]
	v_lshl_add_u64 v[70:71], v[70:71], 0, v[74:75]
	v_and_b32_e32 v244, 31, v194
	v_and_b32_e32 v246, 3, v244
	v_bfe_u32 v245, v244, 2, 2
	v_lshl_add_u32 v246, v245, 3, v246
	v_lshrrev_b32_e32 v245, 4, v244
	v_lshl_add_u32 v246, v245, 5, v246
	v_lshlrev_b32_e32 v246, 12, v246
	v_lshlrev_b32_e32 v245, 2, v244
	v_sub_u32_e32 v246, v246, v245
	v_ashrrev_i32_e32 v247, 31, v246
	v_lshl_add_u64 v[248:249], v[70:71], 0, v[246:247]
	global_load_dword v250, v[248:249], off
	global_load_dword v251, v[248:249], off offset:128
	v_add_u32_e32 v72, 0xffffc000, v66
	global_load_dword v73, v[70:71], off
	v_lshrrev_b32_e32 v70, 4, v72
	v_or_b32_e32 v70, 2, v70
	v_cndmask_b32_e32 v70, v70, v121, vcc
	v_add_u32_e32 v70, s94, v70
	v_mul_lo_u32 v81, v70, s74
	v_add_u32_e32 v70, v81, v120
	v_ashrrev_i32_e32 v71, 31, v70
	v_lshl_add_u64 v[70:71], v[70:71], 2, s[78:79]
	global_load_dword v70, v[70:71], off
	s_andn2_b64 vcc, exec, s[20:21]
	s_waitcnt vmcnt(0)
	v_fmac_f32_e32 v73, v48, v70
	global_store_dword v[68:69], v73, off
	v_or_b32_e32 v68, v122, v124
	v_cndmask_b32_e64 v48, 0, 1, s[20:21]
	v_cmp_ne_u32_e64 s[6:7], 1, v48
	v_cmp_lt_i32_e64 s[10:11], s64, v68
	s_cbranch_vccnz .LBB0_1019
	s_and_saveexec_b64 s[2:3], s[10:11]
	s_xor_b64 s[2:3], exec, s[2:3]
	v_mov_b32_e32 v69, v163
	v_add_u32_e32 v74, 0xffffc000, v68
	v_mov_b32_e32 v75, v163
	v_mov_b64_e32 v[70:71], v[68:69]
	s_or_saveexec_b64 s[2:3], s[2:3]
	v_readlane_b32 s10, v254, 2
	v_readlane_b32 s11, v254, 3
	s_nop 1
	v_mov_b64_e32 v[76:77], s[10:11]
	s_xor_b64 exec, exec, s[2:3]
	v_ashrrev_i32_e32 v69, 31, v68
	v_mov_b64_e32 v[76:77], s[0:1]
	v_mov_b64_e32 v[74:75], v[68:69]
	v_mov_b64_e32 v[70:71], v[68:69]
	s_or_b64 exec, exec, s[2:3]
	s_mov_b64 s[2:3], 0
